# residual-GEMM epilogue de-serialised: loads batched 4 rows at a time, next batch issued before stores (counted vmcnt); helps the 32-workgroup context-row units
# speedup vs baseline: 1.0530x; 1.0099x over previous
.LBB0_144:
	s_lshl_b32 s24, s83, 8
	s_ashr_i32 s25, s24, 31
	s_add_i32 s60, s24, 0xffff8000
	s_cmpk_gt_i32 s83, 0x7f
	s_cselect_b32 s25, 0, s25
	s_cselect_b32 s24, s60, s24
	s_cselect_b32 s61, s51, s49
	s_cselect_b32 s60, s50, s48
	s_cselect_b32 s62, s21, s19
	s_cselect_b32 s63, s20, s18
	s_lshl_b64 s[24:25], s[24:25], 12
	s_add_u32 s60, s60, s24
	s_addc_u32 s61, s61, s25
	s_add_u32 s24, s63, s24
	s_addc_u32 s25, s62, s25
	s_min_i32 s62, s83, 0x80
	s_ashr_i32 s62, s62, 4
	s_mul_hi_i32 s63, s62, 0x9000
	s_mul_i32 s62, s62, 0x9000
	v_lshl_or_b32 v172, s84, 8, v175
	s_add_u32 s62, s70, s62
	s_addc_u32 s63, s71, s63
	v_ashrrev_i32_e32 v173, 31, v172
	v_lshl_add_u64 v[160:161], v[172:173], 2, s[62:63]
	global_load_dwordx4 v[162:165], v[160:161], off offset:16
	global_load_dwordx4 v[166:169], v[160:161], off
	global_load_dwordx4 v[178:181], v[160:161], off offset:528
	global_load_dwordx4 v[188:191], v[160:161], off offset:512
	v_mov_b32_e32 v137, v136
	s_and_b64 vcc, exec, s[40:41]
	s_mov_b32 s92, 0x10000
	s_mov_b32 s93, 0x14000
	s_movk_i32 s88, 0x2ff
	s_movk_i32 s89, 0x600
	v_lshl_add_u64 v[192:193], v[138:139], 0, v[172:173]
	v_lshlrev_b64 v[192:193], 2, v[192:193]
	v_lshl_add_u64 v[194:195], s[60:61], 0, v[192:193]
	global_load_dwordx4 v[214:217], v[194:195], off offset:16
	global_load_dwordx4 v[218:221], v[194:195], off offset:0
	v_lshl_add_u64 v[192:193], v[142:143], 0, v[172:173]
	v_lshlrev_b64 v[192:193], 2, v[192:193]
	v_lshl_add_u64 v[194:195], s[60:61], 0, v[192:193]
	global_load_dwordx4 v[222:225], v[194:195], off offset:16
	global_load_dwordx4 v[226:229], v[194:195], off offset:0
	v_lshl_add_u64 v[192:193], v[144:145], 0, v[172:173]
	v_lshlrev_b64 v[192:193], 2, v[192:193]
	v_lshl_add_u64 v[194:195], s[60:61], 0, v[192:193]
	global_load_dwordx4 v[230:233], v[194:195], off offset:16
	global_load_dwordx4 v[234:237], v[194:195], off offset:0
	v_lshl_add_u64 v[192:193], v[146:147], 0, v[172:173]
	v_lshlrev_b64 v[192:193], 2, v[192:193]
	v_lshl_add_u64 v[194:195], s[60:61], 0, v[192:193]
	global_load_dwordx4 v[238:241], v[194:195], off offset:16
	global_load_dwordx4 v[242:245], v[194:195], off offset:0
	s_waitcnt vmcnt(8)
	v_pk_mul_f32 v[164:165], v[136:137], v[164:165]
	v_pk_mul_f32 v[170:171], v[154:155], v[166:167]
	v_pk_mul_f32 v[166:167], v[154:155], v[162:163]
	v_pk_mul_f32 v[168:169], v[136:137], v[168:169]
	v_pk_mul_f32 v[180:181], v[136:137], v[180:181]
	v_pk_mul_f32 v[178:179], v[154:155], v[178:179]
	v_pk_mul_f32 v[188:189], v[154:155], v[188:189]
	v_pk_mul_f32 v[190:191], v[136:137], v[190:191]
	s_waitcnt vmcnt(0)
	v_pk_fma_f32 v[124:125], v[124:125], v[164:165], v[216:217]
	v_pk_fma_f32 v[122:123], v[122:123], v[166:167], v[214:215]
	v_pk_fma_f32 v[126:127], v[126:127], v[170:171], v[218:219]
	v_pk_fma_f32 v[128:129], v[128:129], v[168:169], v[220:221]
	v_pk_fma_f32 v[116:117], v[116:117], v[164:165], v[224:225]
	v_pk_fma_f32 v[114:115], v[114:115], v[166:167], v[222:223]
	v_pk_fma_f32 v[118:119], v[118:119], v[170:171], v[226:227]
	v_pk_fma_f32 v[120:121], v[120:121], v[168:169], v[228:229]
	v_pk_fma_f32 v[108:109], v[108:109], v[164:165], v[232:233]
	v_pk_fma_f32 v[106:107], v[106:107], v[166:167], v[230:231]
	v_pk_fma_f32 v[110:111], v[110:111], v[170:171], v[234:235]
	v_pk_fma_f32 v[112:113], v[112:113], v[168:169], v[236:237]
	v_pk_fma_f32 v[100:101], v[100:101], v[164:165], v[240:241]
	v_pk_fma_f32 v[98:99], v[98:99], v[166:167], v[238:239]
	v_pk_fma_f32 v[102:103], v[102:103], v[170:171], v[242:243]
	v_pk_fma_f32 v[104:105], v[104:105], v[168:169], v[244:245]
	v_lshl_add_u64 v[192:193], v[140:141], 0, v[172:173]
	v_lshlrev_b64 v[192:193], 2, v[192:193]
	v_lshl_add_u64 v[194:195], s[60:61], 0, v[192:193]
	global_load_dwordx4 v[214:217], v[194:195], off offset:16
	global_load_dwordx4 v[218:221], v[194:195], off offset:0
	v_lshl_add_u64 v[192:193], v[148:149], 0, v[172:173]
	v_lshlrev_b64 v[192:193], 2, v[192:193]
	v_lshl_add_u64 v[194:195], s[60:61], 0, v[192:193]
	global_load_dwordx4 v[222:225], v[194:195], off offset:16
	global_load_dwordx4 v[226:229], v[194:195], off offset:0
	v_lshl_add_u64 v[192:193], v[150:151], 0, v[172:173]
	v_lshlrev_b64 v[192:193], 2, v[192:193]
	v_lshl_add_u64 v[194:195], s[60:61], 0, v[192:193]
	global_load_dwordx4 v[230:233], v[194:195], off offset:16
	global_load_dwordx4 v[234:237], v[194:195], off offset:0
	v_lshl_add_u64 v[192:193], v[152:153], 0, v[172:173]
	v_lshlrev_b64 v[192:193], 2, v[192:193]
	v_lshl_add_u64 v[194:195], s[60:61], 0, v[192:193]
	global_load_dwordx4 v[238:241], v[194:195], off offset:16
	global_load_dwordx4 v[242:245], v[194:195], off offset:0
	v_lshl_add_u64 v[196:197], v[138:139], 0, v[172:173]
	v_lshlrev_b64 v[196:197], 2, v[196:197]
	v_lshl_add_u64 v[196:197], s[24:25], 0, v[196:197]
	global_store_dwordx4 v[196:197], v[122:125], off offset:16
	global_store_dwordx4 v[196:197], v[126:129], off offset:0
	v_lshl_add_u64 v[196:197], v[142:143], 0, v[172:173]
	v_lshlrev_b64 v[196:197], 2, v[196:197]
	v_lshl_add_u64 v[196:197], s[24:25], 0, v[196:197]
	global_store_dwordx4 v[196:197], v[114:117], off offset:16
	global_store_dwordx4 v[196:197], v[118:121], off offset:0
	v_lshl_add_u64 v[196:197], v[144:145], 0, v[172:173]
	v_lshlrev_b64 v[196:197], 2, v[196:197]
	v_lshl_add_u64 v[196:197], s[24:25], 0, v[196:197]
	global_store_dwordx4 v[196:197], v[106:109], off offset:16
	global_store_dwordx4 v[196:197], v[110:113], off offset:0
	v_lshl_add_u64 v[196:197], v[146:147], 0, v[172:173]
	v_lshlrev_b64 v[196:197], 2, v[196:197]
	v_lshl_add_u64 v[196:197], s[24:25], 0, v[196:197]
	global_store_dwordx4 v[196:197], v[98:101], off offset:16
	global_store_dwordx4 v[196:197], v[102:105], off offset:0
	s_waitcnt vmcnt(8)
	v_pk_fma_f32 v[92:93], v[92:93], v[164:165], v[216:217]
	v_pk_fma_f32 v[90:91], v[90:91], v[166:167], v[214:215]
	v_pk_fma_f32 v[94:95], v[94:95], v[170:171], v[218:219]
	v_pk_fma_f32 v[96:97], v[96:97], v[168:169], v[220:221]
	v_pk_fma_f32 v[84:85], v[84:85], v[164:165], v[224:225]
	v_pk_fma_f32 v[82:83], v[82:83], v[166:167], v[222:223]
	v_pk_fma_f32 v[86:87], v[86:87], v[170:171], v[226:227]
	v_pk_fma_f32 v[88:89], v[88:89], v[168:169], v[228:229]
	v_pk_fma_f32 v[76:77], v[76:77], v[164:165], v[232:233]
	v_pk_fma_f32 v[74:75], v[74:75], v[166:167], v[230:231]
	v_pk_fma_f32 v[78:79], v[78:79], v[170:171], v[234:235]
	v_pk_fma_f32 v[80:81], v[80:81], v[168:169], v[236:237]
	v_pk_fma_f32 v[68:69], v[68:69], v[164:165], v[240:241]
	v_pk_fma_f32 v[66:67], v[66:67], v[166:167], v[238:239]
	v_pk_fma_f32 v[70:71], v[70:71], v[170:171], v[242:243]
	v_pk_fma_f32 v[72:73], v[72:73], v[168:169], v[244:245]
	v_lshl_add_u64 v[192:193], v[138:139], 0, v[172:173]
	v_lshlrev_b64 v[192:193], 2, v[192:193]
	v_lshl_add_u64 v[194:195], s[60:61], 0, v[192:193]
	global_load_dwordx4 v[214:217], v[194:195], off offset:528
	global_load_dwordx4 v[218:221], v[194:195], off offset:512
	v_lshl_add_u64 v[192:193], v[142:143], 0, v[172:173]
	v_lshlrev_b64 v[192:193], 2, v[192:193]
	v_lshl_add_u64 v[194:195], s[60:61], 0, v[192:193]
	global_load_dwordx4 v[222:225], v[194:195], off offset:528
	global_load_dwordx4 v[226:229], v[194:195], off offset:512
	v_lshl_add_u64 v[192:193], v[144:145], 0, v[172:173]
	v_lshlrev_b64 v[192:193], 2, v[192:193]
	v_lshl_add_u64 v[194:195], s[60:61], 0, v[192:193]
	global_load_dwordx4 v[230:233], v[194:195], off offset:528
	global_load_dwordx4 v[234:237], v[194:195], off offset:512
	v_lshl_add_u64 v[192:193], v[146:147], 0, v[172:173]
	v_lshlrev_b64 v[192:193], 2, v[192:193]
	v_lshl_add_u64 v[194:195], s[60:61], 0, v[192:193]
	global_load_dwordx4 v[238:241], v[194:195], off offset:528
	global_load_dwordx4 v[242:245], v[194:195], off offset:512
	v_lshl_add_u64 v[196:197], v[140:141], 0, v[172:173]
	v_lshlrev_b64 v[196:197], 2, v[196:197]
	v_lshl_add_u64 v[196:197], s[24:25], 0, v[196:197]
	global_store_dwordx4 v[196:197], v[90:93], off offset:16
	global_store_dwordx4 v[196:197], v[94:97], off offset:0
	v_lshl_add_u64 v[196:197], v[148:149], 0, v[172:173]
	v_lshlrev_b64 v[196:197], 2, v[196:197]
	v_lshl_add_u64 v[196:197], s[24:25], 0, v[196:197]
	global_store_dwordx4 v[196:197], v[82:85], off offset:16
	global_store_dwordx4 v[196:197], v[86:89], off offset:0
	v_lshl_add_u64 v[196:197], v[150:151], 0, v[172:173]
	v_lshlrev_b64 v[196:197], 2, v[196:197]
	v_lshl_add_u64 v[196:197], s[24:25], 0, v[196:197]
	global_store_dwordx4 v[196:197], v[74:77], off offset:16
	global_store_dwordx4 v[196:197], v[78:81], off offset:0
	v_lshl_add_u64 v[196:197], v[152:153], 0, v[172:173]
	v_lshlrev_b64 v[196:197], 2, v[196:197]
	v_lshl_add_u64 v[196:197], s[24:25], 0, v[196:197]
	global_store_dwordx4 v[196:197], v[66:69], off offset:16
	global_store_dwordx4 v[196:197], v[70:73], off offset:0
	s_waitcnt vmcnt(8)
	v_pk_fma_f32 v[60:61], v[60:61], v[180:181], v[216:217]
	v_pk_fma_f32 v[58:59], v[58:59], v[178:179], v[214:215]
	v_pk_fma_f32 v[62:63], v[62:63], v[188:189], v[218:219]
	v_pk_fma_f32 v[64:65], v[64:65], v[190:191], v[220:221]
	v_pk_fma_f32 v[52:53], v[52:53], v[180:181], v[224:225]
	v_pk_fma_f32 v[50:51], v[50:51], v[178:179], v[222:223]
	v_pk_fma_f32 v[54:55], v[54:55], v[188:189], v[226:227]
	v_pk_fma_f32 v[56:57], v[56:57], v[190:191], v[228:229]
	v_pk_fma_f32 v[44:45], v[44:45], v[180:181], v[232:233]
	v_pk_fma_f32 v[42:43], v[42:43], v[178:179], v[230:231]
	v_pk_fma_f32 v[46:47], v[46:47], v[188:189], v[234:235]
	v_pk_fma_f32 v[48:49], v[48:49], v[190:191], v[236:237]
	v_pk_fma_f32 v[36:37], v[36:37], v[180:181], v[240:241]
	v_pk_fma_f32 v[34:35], v[34:35], v[178:179], v[238:239]
	v_pk_fma_f32 v[38:39], v[38:39], v[188:189], v[242:243]
	v_pk_fma_f32 v[40:41], v[40:41], v[190:191], v[244:245]
	v_lshl_add_u64 v[192:193], v[140:141], 0, v[172:173]
	v_lshlrev_b64 v[192:193], 2, v[192:193]
	v_lshl_add_u64 v[194:195], s[60:61], 0, v[192:193]
	global_load_dwordx4 v[214:217], v[194:195], off offset:528
	global_load_dwordx4 v[218:221], v[194:195], off offset:512
	v_lshl_add_u64 v[192:193], v[148:149], 0, v[172:173]
	v_lshlrev_b64 v[192:193], 2, v[192:193]
	v_lshl_add_u64 v[194:195], s[60:61], 0, v[192:193]
	global_load_dwordx4 v[222:225], v[194:195], off offset:528
	global_load_dwordx4 v[226:229], v[194:195], off offset:512
	v_lshl_add_u64 v[192:193], v[150:151], 0, v[172:173]
	v_lshlrev_b64 v[192:193], 2, v[192:193]
	v_lshl_add_u64 v[194:195], s[60:61], 0, v[192:193]
	global_load_dwordx4 v[230:233], v[194:195], off offset:528
	global_load_dwordx4 v[234:237], v[194:195], off offset:512
	v_lshl_add_u64 v[192:193], v[152:153], 0, v[172:173]
	v_lshlrev_b64 v[192:193], 2, v[192:193]
	v_lshl_add_u64 v[194:195], s[60:61], 0, v[192:193]
	global_load_dwordx4 v[238:241], v[194:195], off offset:528
	global_load_dwordx4 v[242:245], v[194:195], off offset:512
	v_lshl_add_u64 v[196:197], v[138:139], 0, v[172:173]
	v_lshlrev_b64 v[196:197], 2, v[196:197]
	v_lshl_add_u64 v[196:197], s[24:25], 0, v[196:197]
	global_store_dwordx4 v[196:197], v[58:61], off offset:528
	global_store_dwordx4 v[196:197], v[62:65], off offset:512
	v_lshl_add_u64 v[196:197], v[142:143], 0, v[172:173]
	v_lshlrev_b64 v[196:197], 2, v[196:197]
	v_lshl_add_u64 v[196:197], s[24:25], 0, v[196:197]
	global_store_dwordx4 v[196:197], v[50:53], off offset:528
	global_store_dwordx4 v[196:197], v[54:57], off offset:512
	v_lshl_add_u64 v[196:197], v[144:145], 0, v[172:173]
	v_lshlrev_b64 v[196:197], 2, v[196:197]
	v_lshl_add_u64 v[196:197], s[24:25], 0, v[196:197]
	global_store_dwordx4 v[196:197], v[42:45], off offset:528
	global_store_dwordx4 v[196:197], v[46:49], off offset:512
	v_lshl_add_u64 v[196:197], v[146:147], 0, v[172:173]
	v_lshlrev_b64 v[196:197], 2, v[196:197]
	v_lshl_add_u64 v[196:197], s[24:25], 0, v[196:197]
	global_store_dwordx4 v[196:197], v[34:37], off offset:528
	global_store_dwordx4 v[196:197], v[38:41], off offset:512
	s_waitcnt vmcnt(8)
	v_pk_fma_f32 v[28:29], v[28:29], v[180:181], v[216:217]
	v_pk_fma_f32 v[26:27], v[26:27], v[178:179], v[214:215]
	v_pk_fma_f32 v[30:31], v[30:31], v[188:189], v[218:219]
	v_pk_fma_f32 v[32:33], v[32:33], v[190:191], v[220:221]
	v_pk_fma_f32 v[20:21], v[20:21], v[180:181], v[224:225]
	v_pk_fma_f32 v[18:19], v[18:19], v[178:179], v[222:223]
	v_pk_fma_f32 v[22:23], v[22:23], v[188:189], v[226:227]
	v_pk_fma_f32 v[24:25], v[24:25], v[190:191], v[228:229]
	v_pk_fma_f32 v[12:13], v[12:13], v[180:181], v[232:233]
	v_pk_fma_f32 v[10:11], v[10:11], v[178:179], v[230:231]
	v_pk_fma_f32 v[14:15], v[14:15], v[188:189], v[234:235]
	v_pk_fma_f32 v[16:17], v[16:17], v[190:191], v[236:237]
	v_pk_fma_f32 v[4:5], v[4:5], v[180:181], v[240:241]
	v_pk_fma_f32 v[2:3], v[2:3], v[178:179], v[238:239]
	v_pk_fma_f32 v[6:7], v[6:7], v[188:189], v[242:243]
	v_pk_fma_f32 v[8:9], v[8:9], v[190:191], v[244:245]
	v_lshl_add_u64 v[196:197], v[140:141], 0, v[172:173]
	v_lshlrev_b64 v[196:197], 2, v[196:197]
	v_lshl_add_u64 v[196:197], s[24:25], 0, v[196:197]
	global_store_dwordx4 v[196:197], v[26:29], off offset:528
	global_store_dwordx4 v[196:197], v[30:33], off offset:512
	v_lshl_add_u64 v[196:197], v[148:149], 0, v[172:173]
	v_lshlrev_b64 v[196:197], 2, v[196:197]
	v_lshl_add_u64 v[196:197], s[24:25], 0, v[196:197]
	global_store_dwordx4 v[196:197], v[18:21], off offset:528
	global_store_dwordx4 v[196:197], v[22:25], off offset:512
	v_lshl_add_u64 v[196:197], v[150:151], 0, v[172:173]
	v_lshlrev_b64 v[196:197], 2, v[196:197]
	v_lshl_add_u64 v[196:197], s[24:25], 0, v[196:197]
	global_store_dwordx4 v[196:197], v[10:13], off offset:528
	global_store_dwordx4 v[196:197], v[14:17], off offset:512
	v_lshl_add_u64 v[196:197], v[152:153], 0, v[172:173]
	v_lshlrev_b64 v[196:197], 2, v[196:197]
	v_lshl_add_u64 v[196:197], s[24:25], 0, v[196:197]
	global_store_dwordx4 v[196:197], v[2:5], off offset:528
	global_store_dwordx4 v[196:197], v[6:9], off offset:512
	s_mov_b64 s[24:25], -1
	s_cbranch_vccnz .LBB0_129
	s_andn2_b64 vcc, exec, s[54:55]
	s_cbranch_vccnz .LBB0_128
	s_barrier
	s_branch .LBB0_128
